# merge K-loops: LDS fragment-read addresses kept in registers and flipped by xor before the barrier (no post-barrier address arithmetic)
# speedup vs baseline: 1.0073x; 1.0073x over previous
.LBB0_243:
	s_cmp_lt_i32 s42, 1
	s_waitcnt lgkmcnt(0)
	s_barrier
	s_cbranch_scc1 .LBB0_250
	v_bfe_u32 v4, v12, 4, 2
	v_ashrrev_i32_e32 v6, 1, v12
	v_lshrrev_b32_e32 v3, 4, v12
	v_and_b32_e32 v5, 15, v12
	v_and_b32_e32 v7, 0xffffffc0, v6
	v_or_b32_e32 v6, 4, v4
	v_and_b32_e32 v2, 64, v12
	v_lshlrev_b32_e32 v128, 12, v4
	v_bitop3_b32 v3, v3, v5, 3 bitop3:0x6c
	v_lshlrev_b32_e32 v129, 12, v6
	v_bitop3_b32 v5, v4, v5, 4 bitop3:0x36
	v_lshlrev_b32_e32 v130, 11, v4
	v_lshlrev_b32_e32 v131, 11, v6
	v_add_u32_e32 v4, v13, v10
	v_mov_b32_e32 v6, 0
	v_add_lshl_u32 v132, v4, v11, 10
	s_mov_b32 s43, 0
	v_lshlrev_b32_e32 v133, 4, v7
	v_lshlrev_b32_e32 v134, 4, v2
	v_lshlrev_b32_e32 v135, 4, v3
	v_lshlrev_b32_e32 v136, 4, v5
	v_mov_b32_e32 v7, v6
	v_mov_b32_e32 v8, v6
	v_mov_b32_e32 v9, v6
	v_mov_b32_e32 v2, v6
	v_mov_b32_e32 v3, v6
	v_mov_b32_e32 v4, v6
	v_mov_b32_e32 v5, v6
	v_mov_b32_e32 v10, v6
	v_mov_b32_e32 v11, v6
	v_mov_b32_e32 v12, v6
	v_mov_b32_e32 v13, v6
	v_mov_b32_e32 v14, v6
	v_mov_b32_e32 v15, v6
	v_mov_b32_e32 v16, v6
	v_mov_b32_e32 v17, v6
	v_mov_b32_e32 v18, v6
	v_mov_b32_e32 v19, v6
	v_mov_b32_e32 v20, v6
	v_mov_b32_e32 v21, v6
	v_mov_b32_e32 v22, v6
	v_mov_b32_e32 v23, v6
	v_mov_b32_e32 v24, v6
	v_mov_b32_e32 v25, v6
	v_mov_b32_e32 v26, v6
	v_mov_b32_e32 v27, v6
	v_mov_b32_e32 v28, v6
	v_mov_b32_e32 v29, v6
	v_mov_b32_e32 v30, v6
	v_mov_b32_e32 v31, v6
	v_mov_b32_e32 v32, v6
	v_mov_b32_e32 v33, v6
	v_mov_b32_e32 v44, v6
	v_mov_b32_e32 v45, v6
	v_mov_b32_e32 v46, v6
	v_mov_b32_e32 v47, v6
	v_mov_b32_e32 v48, v6
	v_mov_b32_e32 v49, v6
	v_mov_b32_e32 v50, v6
	v_mov_b32_e32 v51, v6
	v_mov_b32_e32 v60, v6
	v_mov_b32_e32 v61, v6
	v_mov_b32_e32 v62, v6
	v_mov_b32_e32 v63, v6
	v_mov_b32_e32 v64, v6
	v_mov_b32_e32 v65, v6
	v_mov_b32_e32 v66, v6
	v_mov_b32_e32 v67, v6
	v_mov_b32_e32 v72, v6
	v_mov_b32_e32 v73, v6
	v_mov_b32_e32 v74, v6
	v_mov_b32_e32 v75, v6
	v_mov_b32_e32 v80, v6
	v_mov_b32_e32 v81, v6
	v_mov_b32_e32 v82, v6
	v_mov_b32_e32 v83, v6
	v_mov_b32_e32 v92, v6
	v_mov_b32_e32 v93, v6
	v_mov_b32_e32 v94, v6
	v_mov_b32_e32 v95, v6
	v_mov_b32_e32 v96, v6
	v_mov_b32_e32 v97, v6
	v_mov_b32_e32 v98, v6
	v_mov_b32_e32 v99, v6
	v_add3_u32 v237, v130, v134, v135
	v_add3_u32 v238, v128, v133, v135
	v_add3_u32 v239, v129, v133, v136
	v_add3_u32 v240, v131, v134, v136
	v_add_u32_e32 v237, 0x10000, v237
	v_add_u32_e32 v240, 0x10000, v240
.LBB0_245:
	s_and_b32 s45, s43, 1
	ds_read_b128 v[84:87], v237
	ds_read_b128 v[88:91], v237 offset:256
	ds_read_b128 v[100:103], v237 offset:512
	ds_read_b128 v[104:107], v237 offset:768
	ds_read_b128 v[108:111], v238
	ds_read_b128 v[112:115], v238 offset:256
	ds_read_b128 v[116:119], v238 offset:512
	ds_read_b128 v[120:123], v238 offset:768
	s_waitcnt lgkmcnt(3)
	v_mfma_f32_16x16x32_f16 v[96:99], v[84:87], v[108:111], v[96:99]
	v_mfma_f32_16x16x32_f16 v[92:95], v[88:91], v[108:111], v[92:95]
	v_mfma_f32_16x16x32_f16 v[80:83], v[100:103], v[108:111], v[80:83]
	v_mfma_f32_16x16x32_f16 v[72:75], v[104:107], v[108:111], v[72:75]
	s_waitcnt lgkmcnt(2)
	v_mfma_f32_16x16x32_f16 v[64:67], v[84:87], v[112:115], v[64:67]
	v_mfma_f32_16x16x32_f16 v[60:63], v[88:91], v[112:115], v[60:63]
	v_mfma_f32_16x16x32_f16 v[48:51], v[100:103], v[112:115], v[48:51]
	v_mfma_f32_16x16x32_f16 v[44:47], v[104:107], v[112:115], v[44:47]
	s_waitcnt lgkmcnt(1)
	v_mfma_f32_16x16x32_f16 v[30:33], v[84:87], v[116:119], v[30:33]
	v_mfma_f32_16x16x32_f16 v[26:29], v[88:91], v[116:119], v[26:29]
	v_mfma_f32_16x16x32_f16 v[22:25], v[100:103], v[116:119], v[22:25]
	v_mfma_f32_16x16x32_f16 v[18:21], v[104:107], v[116:119], v[18:21]
	s_waitcnt lgkmcnt(0)
	v_mfma_f32_16x16x32_f16 v[14:17], v[84:87], v[120:123], v[14:17]
	v_mfma_f32_16x16x32_f16 v[10:13], v[88:91], v[120:123], v[10:13]
	v_mfma_f32_16x16x32_f16 v[2:5], v[100:103], v[120:123], v[2:5]
	v_mfma_f32_16x16x32_f16 v[6:9], v[104:107], v[120:123], v[6:9]
	ds_read_b128 v[104:107], v240
	ds_read_b128 v[108:111], v240 offset:256
	ds_read_b128 v[100:103], v240 offset:512
	ds_read_b128 v[84:87], v240 offset:768
	ds_read_b128 v[120:123], v239
	ds_read_b128 v[116:119], v239 offset:256
	ds_read_b128 v[112:115], v239 offset:512
	ds_read_b128 v[88:91], v239 offset:768
	v_xor_b32_e32 v237, 0x4000, v237
	v_xor_b32_e32 v238, 0x8000, v238
	v_xor_b32_e32 v239, 0x8000, v239
	v_xor_b32_e32 v240, 0x4000, v240
	s_add_i32 s44, s43, 1
	s_cmp_ge_i32 s44, s42
	s_cbranch_scc1 .Ls1_cold
	s_xor_b32 s45, s45, 1
	v_lshl_add_u32 v254, s45, 15, v126
	v_lshl_add_u32 v255, s45, 14, v127
	s_add_i32 s43, s43, 2
	s_cmp_ge_i32 s43, s42
	s_cbranch_scc1 .Ls1_warm
	v_add_u32_e32 v246, v124, v125
	v_add_u32_e32 v247, v124, v132
	v_lshlrev_b32_e32 v246, 1, v246
	v_lshlrev_b32_e32 v247, 1, v247
	v_add_u32_e32 v248, 0x20000, v246
	v_add_u32_e32 v249, 0x40000, v246
	v_add_u32_e32 v250, 0x60000, v246
	v_add_u32_e32 v251, 0x20000, v247
	s_waitcnt vmcnt(5)
	ds_write_b128 v254, v[36:39]
	global_load_dwordx4 v[36:39], v246, s[40:41] offset:256
	s_waitcnt vmcnt(5)
	ds_write_b128 v254, v[40:43] offset:1024
	global_load_dwordx4 v[40:43], v248, s[40:41] offset:256
	s_waitcnt lgkmcnt(5)
	v_mfma_f32_16x16x32_f16 v[96:99], v[104:107], v[120:123], v[96:99]
	v_add_u32_e32 v132, 64, v132
	v_add_u32_e32 v125, 64, v125
	s_cmp_lg_u32 s42, s44
	v_mfma_f32_16x16x32_f16 v[92:95], v[108:111], v[120:123], v[92:95]
	v_mfma_f32_16x16x32_f16 v[80:83], v[100:103], v[120:123], v[80:83]
	v_mfma_f32_16x16x32_f16 v[72:75], v[84:87], v[120:123], v[72:75]
	s_waitcnt vmcnt(5)
	ds_write_b128 v254, v[52:55] offset:2048
	global_load_dwordx4 v[52:55], v249, s[40:41] offset:256
	s_waitcnt vmcnt(5)
	ds_write_b128 v254, v[56:59] offset:3072
	global_load_dwordx4 v[56:59], v250, s[40:41] offset:256
	s_waitcnt lgkmcnt(6)
	v_mfma_f32_16x16x32_f16 v[64:67], v[104:107], v[116:119], v[64:67]
	v_mfma_f32_16x16x32_f16 v[60:63], v[108:111], v[116:119], v[60:63]
	v_mfma_f32_16x16x32_f16 v[48:51], v[100:103], v[116:119], v[48:51]
	v_mfma_f32_16x16x32_f16 v[44:47], v[84:87], v[116:119], v[44:47]
	s_waitcnt vmcnt(5)
	ds_write_b128 v255, v[68:71]
	global_load_dwordx4 v[68:71], v247, s[38:39] offset:256
	s_waitcnt lgkmcnt(6)
	v_mfma_f32_16x16x32_f16 v[30:33], v[104:107], v[112:115], v[30:33]
	v_mfma_f32_16x16x32_f16 v[26:29], v[108:111], v[112:115], v[26:29]
	v_mfma_f32_16x16x32_f16 v[22:25], v[100:103], v[112:115], v[22:25]
	v_mfma_f32_16x16x32_f16 v[18:21], v[84:87], v[112:115], v[18:21]
	s_waitcnt vmcnt(5)
	ds_write_b128 v255, v[76:79] offset:1024
	global_load_dwordx4 v[76:79], v251, s[38:39] offset:256
	s_waitcnt lgkmcnt(6)
	v_mfma_f32_16x16x32_f16 v[14:17], v[104:107], v[88:91], v[14:17]
	v_mfma_f32_16x16x32_f16 v[10:13], v[108:111], v[88:91], v[10:13]
	v_mfma_f32_16x16x32_f16 v[2:5], v[100:103], v[88:91], v[2:5]
	v_mfma_f32_16x16x32_f16 v[6:9], v[84:87], v[88:91], v[6:9]
	s_waitcnt lgkmcnt(0)
	s_barrier

.LBB0_253:
	s_cmp_lt_i32 s24, 1
	s_waitcnt lgkmcnt(0)
	s_barrier
	s_cbranch_scc1 .LBB0_260
	v_bfe_u32 v70, v86, 4, 2
	v_ashrrev_i32_e32 v76, 1, v86
	v_lshrrev_b32_e32 v69, 4, v86
	v_and_b32_e32 v71, 15, v86
	v_and_b32_e32 v77, 0xffffffc0, v76
	v_or_b32_e32 v76, 4, v70
	v_and_b32_e32 v68, 64, v86
	v_lshlrev_b32_e32 v226, 12, v70
	v_bitop3_b32 v69, v69, v71, 3 bitop3:0x6c
	v_lshlrev_b32_e32 v227, 12, v76
	v_bitop3_b32 v71, v70, v71, 4 bitop3:0x36
	v_lshlrev_b32_e32 v228, 11, v70
	v_lshlrev_b32_e32 v229, 11, v76
	v_add_u32_e32 v70, v87, v84
	v_mov_b32_e32 v76, 0
	v_add_lshl_u32 v230, v70, v85, 9
	s_mov_b32 s59, 0
	v_lshlrev_b32_e32 v231, 4, v77
	v_lshlrev_b32_e32 v232, 4, v68
	v_lshlrev_b32_e32 v233, 4, v69
	v_lshlrev_b32_e32 v234, 4, v71
	v_mov_b32_e32 v77, v76
	v_mov_b32_e32 v78, v76
	v_mov_b32_e32 v79, v76
	v_mov_b32_e32 v68, v76
	v_mov_b32_e32 v69, v76
	v_mov_b32_e32 v70, v76
	v_mov_b32_e32 v71, v76
	v_mov_b32_e32 v84, v76
	v_mov_b32_e32 v85, v76
	v_mov_b32_e32 v86, v76
	v_mov_b32_e32 v87, v76
	v_mov_b32_e32 v88, v76
	v_mov_b32_e32 v89, v76
	v_mov_b32_e32 v90, v76
	v_mov_b32_e32 v91, v76
	v_mov_b32_e32 v100, v76
	v_mov_b32_e32 v101, v76
	v_mov_b32_e32 v102, v76
	v_mov_b32_e32 v103, v76
	v_mov_b32_e32 v104, v76
	v_mov_b32_e32 v105, v76
	v_mov_b32_e32 v106, v76
	v_mov_b32_e32 v107, v76
	v_mov_b32_e32 v108, v76
	v_mov_b32_e32 v109, v76
	v_mov_b32_e32 v110, v76
	v_mov_b32_e32 v111, v76
	v_mov_b32_e32 v112, v76
	v_mov_b32_e32 v113, v76
	v_mov_b32_e32 v114, v76
	v_mov_b32_e32 v115, v76
	v_mov_b32_e32 v116, v76
	v_mov_b32_e32 v117, v76
	v_mov_b32_e32 v118, v76
	v_mov_b32_e32 v119, v76
	v_mov_b32_e32 v120, v76
	v_mov_b32_e32 v121, v76
	v_mov_b32_e32 v122, v76
	v_mov_b32_e32 v123, v76
	v_mov_b32_e32 v124, v76
	v_mov_b32_e32 v125, v76
	v_mov_b32_e32 v126, v76
	v_mov_b32_e32 v127, v76
	v_mov_b32_e32 v128, v76
	v_mov_b32_e32 v129, v76
	v_mov_b32_e32 v130, v76
	v_mov_b32_e32 v131, v76
	v_mov_b32_e32 v132, v76
	v_mov_b32_e32 v133, v76
	v_mov_b32_e32 v134, v76
	v_mov_b32_e32 v135, v76
	v_mov_b32_e32 v136, v76
	v_mov_b32_e32 v137, v76
	v_mov_b32_e32 v138, v76
	v_mov_b32_e32 v139, v76
	v_mov_b32_e32 v140, v76
	v_mov_b32_e32 v141, v76
	v_mov_b32_e32 v142, v76
	v_mov_b32_e32 v143, v76
	v_mov_b32_e32 v144, v76
	v_mov_b32_e32 v145, v76
	v_mov_b32_e32 v146, v76
	v_mov_b32_e32 v147, v76
	v_add3_u32 v237, v228, v232, v233
	v_add3_u32 v238, v226, v231, v233
	v_add3_u32 v239, v227, v231, v234
	v_add3_u32 v240, v229, v232, v234
	v_add_u32_e32 v237, 0x10000, v237
	v_add_u32_e32 v240, 0x10000, v240
.LBB0_255:
	s_and_b32 s61, s59, 1
	ds_read_b128 v[172:175], v237
	ds_read_b128 v[176:179], v237 offset:256
	ds_read_b128 v[180:183], v237 offset:512
	ds_read_b128 v[184:187], v237 offset:768
	ds_read_b128 v[188:191], v238
	ds_read_b128 v[192:195], v238 offset:256
	ds_read_b128 v[196:199], v238 offset:512
	ds_read_b128 v[200:203], v238 offset:768
	s_waitcnt lgkmcnt(3)
	v_mfma_f32_16x16x32_f16 v[144:147], v[172:175], v[188:191], v[144:147]
	v_mfma_f32_16x16x32_f16 v[140:143], v[176:179], v[188:191], v[140:143]
	v_mfma_f32_16x16x32_f16 v[136:139], v[180:183], v[188:191], v[136:139]
	v_mfma_f32_16x16x32_f16 v[132:135], v[184:187], v[188:191], v[132:135]
	s_waitcnt lgkmcnt(2)
	v_mfma_f32_16x16x32_f16 v[128:131], v[172:175], v[192:195], v[128:131]
	v_mfma_f32_16x16x32_f16 v[124:127], v[176:179], v[192:195], v[124:127]
	v_mfma_f32_16x16x32_f16 v[120:123], v[180:183], v[192:195], v[120:123]
	v_mfma_f32_16x16x32_f16 v[116:119], v[184:187], v[192:195], v[116:119]
	s_waitcnt lgkmcnt(1)
	v_mfma_f32_16x16x32_f16 v[112:115], v[172:175], v[196:199], v[112:115]
	v_mfma_f32_16x16x32_f16 v[108:111], v[176:179], v[196:199], v[108:111]
	v_mfma_f32_16x16x32_f16 v[104:107], v[180:183], v[196:199], v[104:107]
	v_mfma_f32_16x16x32_f16 v[100:103], v[184:187], v[196:199], v[100:103]
	s_waitcnt lgkmcnt(0)
	v_mfma_f32_16x16x32_f16 v[88:91], v[172:175], v[200:203], v[88:91]
	v_mfma_f32_16x16x32_f16 v[84:87], v[176:179], v[200:203], v[84:87]
	v_mfma_f32_16x16x32_f16 v[68:71], v[180:183], v[200:203], v[68:71]
	v_mfma_f32_16x16x32_f16 v[76:79], v[184:187], v[200:203], v[76:79]
	ds_read_b128 v[184:187], v240
	ds_read_b128 v[188:191], v240 offset:256
	ds_read_b128 v[180:183], v240 offset:512
	ds_read_b128 v[172:175], v240 offset:768
	ds_read_b128 v[200:203], v239
	ds_read_b128 v[196:199], v239 offset:256
	ds_read_b128 v[192:195], v239 offset:512
	ds_read_b128 v[176:179], v239 offset:768
	v_xor_b32_e32 v237, 0x4000, v237
	v_xor_b32_e32 v238, 0x8000, v238
	v_xor_b32_e32 v239, 0x8000, v239
	v_xor_b32_e32 v240, 0x4000, v240
	s_add_i32 s60, s59, 1
	s_cmp_ge_i32 s60, s24
	s_cbranch_scc1 .Ls2_cold
	s_xor_b32 s61, s61, 1
	v_lshl_add_u32 v254, s61, 15, v210
	v_lshl_add_u32 v255, s61, 14, v211
	s_add_i32 s59, s59, 2
	s_cmp_ge_i32 s59, s24
	s_cbranch_scc1 .Ls2_warm
	v_add_u32_e32 v246, v208, v209
	v_add_u32_e32 v247, v208, v230
	v_lshlrev_b32_e32 v246, 1, v246
	v_lshlrev_b32_e32 v247, 1, v247
	v_add_u32_e32 v248, 0x7c000, v246
	v_add_u32_e32 v249, 0xf8000, v246
	v_add_u32_e32 v250, 0x174000, v246
	v_add_u32_e32 v251, 0x10000, v247
	s_waitcnt vmcnt(5)
	ds_write_b128 v254, v[148:151]
	global_load_dwordx4 v[148:151], v246, s[38:39] offset:256
	s_waitcnt vmcnt(5)
	ds_write_b128 v254, v[152:155] offset:1024
	global_load_dwordx4 v[152:155], v248, s[38:39] offset:256
	s_waitcnt lgkmcnt(5)
	v_mfma_f32_16x16x32_f16 v[144:147], v[184:187], v[200:203], v[144:147]
	v_add_u32_e32 v230, 64, v230
	v_add_u32_e32 v209, 64, v209
	s_cmp_lg_u32 s24, s60
	v_mfma_f32_16x16x32_f16 v[140:143], v[188:191], v[200:203], v[140:143]
	v_mfma_f32_16x16x32_f16 v[136:139], v[180:183], v[200:203], v[136:139]
	v_mfma_f32_16x16x32_f16 v[132:135], v[172:175], v[200:203], v[132:135]
	s_waitcnt vmcnt(5)
	ds_write_b128 v254, v[156:159] offset:2048
	global_load_dwordx4 v[156:159], v249, s[38:39] offset:256
	s_waitcnt vmcnt(5)
	ds_write_b128 v254, v[160:163] offset:3072
	global_load_dwordx4 v[160:163], v250, s[38:39] offset:256
	s_waitcnt lgkmcnt(6)
	v_mfma_f32_16x16x32_f16 v[128:131], v[184:187], v[196:199], v[128:131]
	v_mfma_f32_16x16x32_f16 v[124:127], v[188:191], v[196:199], v[124:127]
	v_mfma_f32_16x16x32_f16 v[120:123], v[180:183], v[196:199], v[120:123]
	v_mfma_f32_16x16x32_f16 v[116:119], v[172:175], v[196:199], v[116:119]
	s_waitcnt vmcnt(5)
	ds_write_b128 v255, v[164:167]
	global_load_dwordx4 v[164:167], v247, s[44:45] offset:256
	s_waitcnt lgkmcnt(6)
	v_mfma_f32_16x16x32_f16 v[112:115], v[184:187], v[192:195], v[112:115]
	v_mfma_f32_16x16x32_f16 v[108:111], v[188:191], v[192:195], v[108:111]
	v_mfma_f32_16x16x32_f16 v[104:107], v[180:183], v[192:195], v[104:107]
	v_mfma_f32_16x16x32_f16 v[100:103], v[172:175], v[192:195], v[100:103]
	s_waitcnt vmcnt(5)
	ds_write_b128 v255, v[168:171] offset:1024
	global_load_dwordx4 v[168:171], v251, s[44:45] offset:256
	s_waitcnt lgkmcnt(6)
	v_mfma_f32_16x16x32_f16 v[88:91], v[184:187], v[176:179], v[88:91]
	v_mfma_f32_16x16x32_f16 v[84:87], v[188:191], v[176:179], v[84:87]
	v_mfma_f32_16x16x32_f16 v[68:71], v[180:183], v[176:179], v[68:71]
	v_mfma_f32_16x16x32_f16 v[76:79], v[172:175], v[176:179], v[76:79]
	s_waitcnt lgkmcnt(0)
	s_barrier
